# S1: dt_acum block moved behind the conv load issue for waves 0-3 (temporaries renamed) so its latency chain overlaps the conv loads
# baseline (speedup 1.0000x reference)
; __device__ __forceinline__ const float* inp(const Params& p, int i) { asm volatile("" : "+s"(i)); return p.in[i]; }
; __device__ __forceinline__ float bfv(const u32x4& v, int j) { const unsigned w = v[j >> 1]; return (j & 1) ? bf_hi(w) : bf_lo(w); }
; __device__ void phase_s1(const Params& p, int layer, unsigned char* lds) {
;     ...
;             const int t2 = tid - 384, rr = t2 & 7, cgi = t2 >> 3, l0 = rr * 8, ch0 = g * 128 + cgi * 8;
;             const float* scw = inp(p, 11) + (size_t)layer * 3 * 1024 + ch0;
;             float w[3][8];
; #pragma unroll
;             for (int k = 0; k < 3; ++k) { const f32x4 a = *(const f32x4*)(scw + k * 1024), bb = *(const f32x4*)(scw + k * 1024 + 4);
; #pragma unroll
;                 for (int j = 0; j < 4; ++j) { w[k][j] = a[j]; w[k][4 + j] = bb[j]; } }
;             float um2[8], um1[8], u0[8];
; #pragma unroll
;             for (int i = 0; i < 10; ++i) {
;                 const int lrow = l0 - 2 + i;
; #pragma unroll
;                 for (int j = 0; j < 8; ++j) { um2[j] = um1[j]; um1[j] = u0[j]; }
;                 if (lrow >= 0 || (c > 0 && c < NPCH)) {
;                     const bf16_t* rp = proj + (size_t)(row0 + lrow) * PROJ_LD + ch0;
;                     const u32x4 cv = *(const u32x4*)(rp + 1024), xv = *(const u32x4*)(rp + 2048);
; #pragma unroll
;                     for (int j = 0; j < 8; ++j) u0[j] = bfv(cv, j) * bfv(xv, j);
;                 } else if (c == 0) {
; #pragma unroll
;                     for (int j = 0; j < 8; ++j) u0[j] = 0.f;
;                 } else {
;                     const float* hp = inp(p, 2) + (((size_t)layer * 8 + (c - NPCH)) * 2 + (2 + lrow)) * 1024 + ch0;
;                     const f32x4 a = *(const f32x4*)hp, bb = *(const f32x4*)(hp + 4);
; #pragma unroll
;                     for (int j = 0; j < 4; ++j) { u0[j] = a[j]; u0[4 + j] = bb[j]; }
;                 }
.LBB0_334:
	s_and_saveexec_b64 s[4:5], s[54:55]
	s_xor_b64 s[80:81], exec, s[4:5]
	s_cbranch_execz .LBB0_350
	s_mov_b32 s4, 11
	s_ashr_i32 s5, s4, 31
	s_lshl_b64 s[4:5], s[4:5], 3
	s_add_u32 s4, s0, s4
	s_addc_u32 s5, s1, s5
	s_load_dwordx2 s[4:5], s[4:5], 0x0
	s_mul_i32 s28, s12, 0x3000
	v_lshl_add_u32 v132, s2, 7, v111
	v_sub_co_u32_e64 v28, s[64:65], s87, v171
	s_waitcnt lgkmcnt(0)
	s_add_u32 s4, s4, s28
	s_mul_hi_i32 s28, s12, 0x3000
	s_addc_u32 s5, s5, s28
	v_lshl_add_u64 v[4:5], v[132:133], 2, s[4:5]
	s_mov_b64 s[4:5], 0x1000
	v_lshl_add_u64 v[6:7], v[4:5], 0, s[4:5]
	s_movk_i32 s4, 0x2000
	v_add_co_u32_e32 v8, vcc, s4, v4
	s_mov_b64 s[4:5], 0x2000
	global_load_dwordx4 v[12:15], v[4:5], off offset:16
	global_load_dwordx4 v[16:19], v[4:5], off
	v_addc_co_u32_e32 v9, vcc, 0, v5, vcc
	v_lshl_add_u64 v[4:5], v[4:5], 0, s[4:5]
	global_load_dwordx4 v[24:27], v[8:9], off offset:-4096
	s_nop 0
	global_load_dwordx4 v[8:11], v[8:9], off
	s_nop 0
	global_load_dwordx4 v[20:23], v[6:7], off offset:16
	s_nop 0
	global_load_dwordx4 v[4:7], v[4:5], off offset:16
	v_readlane_b32 s98, v252, 19
	v_readlane_b32 s99, v252, 20
	v_add_u32_e32 v100, s21, v113
	s_nop 1
	v_lshl_add_u64 v[102:103], v[132:133], 1, s[98:99]
	s_mov_b64 s[100:101], 0x4800
	v_mad_i64_i32 v[100:101], vcc, v100, s35, v[102:103]
	v_add_co_u32_e32 v102, vcc, s36, v100
	s_nop 1
	v_addc_co_u32_e32 v103, vcc, 0, v101, vcc
	global_load_dwordx4 v[172:175], v[100:101], off offset:2048
	global_load_dwordx4 v[212:215], v[102:103], off
	v_lshl_add_u64 v[100:101], v[100:101], 0, s[100:101]
	v_lshl_add_u64 v[102:103], v[102:103], 0, s[100:101]
	global_load_dwordx4 v[176:179], v[100:101], off offset:2048
	global_load_dwordx4 v[216:219], v[102:103], off
	v_lshl_add_u64 v[100:101], v[100:101], 0, s[100:101]
	v_lshl_add_u64 v[102:103], v[102:103], 0, s[100:101]
	global_load_dwordx4 v[180:183], v[100:101], off offset:2048
	global_load_dwordx4 v[220:223], v[102:103], off
	global_load_dwordx4 v[144:147], v[100:101], off
	v_lshl_add_u64 v[100:101], v[100:101], 0, s[100:101]
	v_lshl_add_u64 v[102:103], v[102:103], 0, s[100:101]
	global_load_dwordx4 v[184:187], v[100:101], off offset:2048
	global_load_dwordx4 v[224:227], v[102:103], off
	global_load_dwordx4 v[148:151], v[100:101], off
	v_lshl_add_u64 v[100:101], v[100:101], 0, s[100:101]
	v_lshl_add_u64 v[102:103], v[102:103], 0, s[100:101]
	global_load_dwordx4 v[188:191], v[100:101], off offset:2048
	global_load_dwordx4 v[228:231], v[102:103], off
	global_load_dwordx4 v[152:155], v[100:101], off
	v_lshl_add_u64 v[100:101], v[100:101], 0, s[100:101]
	v_lshl_add_u64 v[102:103], v[102:103], 0, s[100:101]
	global_load_dwordx4 v[192:195], v[100:101], off offset:2048
	global_load_dwordx4 v[232:235], v[102:103], off
	global_load_dwordx4 v[156:159], v[100:101], off
	v_lshl_add_u64 v[100:101], v[100:101], 0, s[100:101]
	v_lshl_add_u64 v[102:103], v[102:103], 0, s[100:101]
	global_load_dwordx4 v[196:199], v[100:101], off offset:2048
	global_load_dwordx4 v[236:239], v[102:103], off
	global_load_dwordx4 v[72:75], v[100:101], off
	v_lshl_add_u64 v[100:101], v[100:101], 0, s[100:101]
	v_lshl_add_u64 v[102:103], v[102:103], 0, s[100:101]
	global_load_dwordx4 v[200:203], v[100:101], off offset:2048
	global_load_dwordx4 v[240:243], v[102:103], off
	global_load_dwordx4 v[76:79], v[100:101], off
	v_lshl_add_u64 v[100:101], v[100:101], 0, s[100:101]
	v_lshl_add_u64 v[102:103], v[102:103], 0, s[100:101]
	global_load_dwordx4 v[204:207], v[100:101], off offset:2048
	global_load_dwordx4 v[244:247], v[102:103], off
	global_load_dwordx4 v[80:83], v[100:101], off
	v_lshl_add_u64 v[100:101], v[100:101], 0, s[100:101]
	v_lshl_add_u64 v[102:103], v[102:103], 0, s[100:101]
	global_load_dwordx4 v[208:211], v[100:101], off offset:2048
	global_load_dwordx4 v[140:143], v[102:103], off
	global_load_dwordx4 v[84:87], v[100:101], off
	s_add_i32 s4, s87, -1
	s_cmpk_gt_u32 s4, 0x7e
	s_cselect_b64 s[4:5], -1, 0
	s_cmp_gt_u32 s86, 7
	v_ashrrev_i32_e32 v29, 31, v28
	s_cselect_b64 s[66:67], -1, 0
	v_readfirstlane_b32 s29, v28
	v_lshl_add_u64 v[28:29], s[70:71], 0, v[28:29]
	v_lshlrev_b64 v[46:47], 13, v[28:29]
	s_xor_b64 s[52:53], s[58:59], -1
	v_cndmask_b32_e64 v28, 0, 1, s[66:67]
	s_and_b64 s[52:53], s[52:53], s[4:5]
	v_cmp_ne_u32_e64 s[66:67], 1, v28
	s_waitcnt vmcnt(0)
	s_and_saveexec_b64 s[4:5], s[52:53]
	s_xor_b64 s[4:5], exec, s[4:5]
	s_cbranch_execz .LBB0_338
	v_mov_b32_e32 v39, 0
	s_and_b64 vcc, exec, s[66:67]
	v_mov_b32_e32 v38, 0
	v_mov_b32_e32 v37, 0
	v_mov_b32_e32 v36, 0
	v_mov_b32_e32 v43, 0
	v_mov_b32_e32 v42, 0
	v_mov_b32_e32 v41, 0
	v_mov_b32_e32 v40, 0
	s_cbranch_vccnz .LBB0_338
	s_mov_b32 s82, 2
	s_ashr_i32 s83, s82, 31
	s_lshl_b64 s[82:83], s[82:83], 3
	s_add_u32 s82, s0, s82
	s_addc_u32 s83, s1, s83
	s_load_dwordx2 s[82:83], s[82:83], 0x0
	s_waitcnt lgkmcnt(0)
	v_lshl_add_u64 v[28:29], s[82:83], 0, v[46:47]
	v_lshl_add_u64 v[28:29], v[132:133], 2, v[28:29]
	global_load_dwordx4 v[40:43], v[28:29], off
	global_load_dwordx4 v[36:39], v[28:29], off offset:16

; __device__ __forceinline__ const float* inp(const Params& p, int i) { asm volatile("" : "+s"(i)); return p.in[i]; }
; __device__ void phase_s1(const Params& p, int layer, unsigned char* lds) {
;     ...
;         if (wave < 4) {
;             const int h = g * 4 + wave; float dtv, acum, total;
;             dt_acum(p, layer, c, h, lane, dtv, acum, total);
;             s_w[wave * 64 + lane] = dtv * __expf(total - acum);
;             if (lane == 0) DEC[c * 32 + h] = __expf(total);
;     ...
;             u32x4 rows[11];
; #pragma unroll
;             for (int i = 0; i < 11; ++i) rows[i] = fetch_xbc8(proj, hist, c, l0 - 3 + i, col);
;             const float* cw = inp(p, 12) + (size_t)layer * 4 * 4096 + col; const float* cb = inp(p, 13) + (size_t)layer * 4096 + col;
;             float w[4][8], b[8];
; #pragma unroll
;             for (int k = 0; k < 4; ++k) { const f32x4 a = *(const f32x4*)(cw + k * 4096), bb = *(const f32x4*)(cw + k * 4096 + 4);
; #pragma unroll
;                 for (int j = 0; j < 4; ++j) { w[k][j] = a[j]; w[k][4 + j] = bb[j]; } }
;             { const f32x4 a = *(const f32x4*)cb, bb = *(const f32x4*)(cb + 4);
; #pragma unroll
;               for (int j = 0; j < 4; ++j) { b[j] = a[j]; b[4 + j] = bb[j]; } }
.LBB0_366:
	s_or_b64 exec, exec, s[4:5]
	v_readlane_b32 s4, v252, 19
	v_readlane_b32 s5, v252, 20
	v_or_b32_e32 v16, s21, v112
	v_lshlrev_b64 v[30:31], 1, v[48:49]
	v_mov_b64_e32 v[28:29], s[4:5]
	v_mad_i64_i32 v[16:17], s[4:5], v16, s35, v[28:29]
	v_lshl_add_u64 v[16:17], v[16:17], 0, v[30:31]
	v_or_b32_e32 v18, s21, v124
	v_add_co_u32_e32 v16, vcc, 0x2000, v16
	v_mad_i64_i32 v[18:19], s[4:5], v18, s35, v[28:29]
	s_nop 0
	v_addc_co_u32_e32 v17, vcc, 0, v17, vcc
	v_lshl_add_u64 v[18:19], v[18:19], 0, v[30:31]
	v_or_b32_e32 v24, s21, v123
	v_add_co_u32_e32 v20, vcc, 0x2000, v18
	v_mad_i64_i32 v[24:25], s[4:5], v24, s35, v[28:29]
	s_nop 0
	v_addc_co_u32_e32 v21, vcc, 0, v19, vcc
	v_lshl_add_u64 v[24:25], v[24:25], 0, v[30:31]
	v_or_b32_e32 v26, s21, v125
	v_add_co_u32_e32 v24, vcc, 0x2000, v24
	v_mad_i64_i32 v[26:27], s[4:5], v26, s35, v[28:29]
	s_nop 0
	v_addc_co_u32_e32 v25, vcc, 0, v25, vcc
	v_lshl_add_u64 v[26:27], v[26:27], 0, v[30:31]
	v_or_b32_e32 v36, s21, v126
	v_add_co_u32_e32 v32, vcc, 0x2000, v26
	v_mad_i64_i32 v[36:37], s[4:5], v36, s35, v[28:29]
	s_nop 0
	v_addc_co_u32_e32 v33, vcc, 0, v27, vcc
	v_lshl_add_u64 v[36:37], v[36:37], 0, v[30:31]
	v_or_b32_e32 v38, s21, v127
	v_add_co_u32_e32 v36, vcc, 0x2000, v36
	v_mad_i64_i32 v[38:39], s[4:5], v38, s35, v[28:29]
	s_nop 0
	v_addc_co_u32_e32 v37, vcc, 0, v37, vcc
	v_lshl_add_u64 v[38:39], v[38:39], 0, v[30:31]
	v_or_b32_e32 v44, s21, v128
	v_add_co_u32_e32 v38, vcc, 0x2000, v38
	v_mad_i64_i32 v[44:45], s[4:5], v44, s35, v[28:29]
	s_nop 0
	v_addc_co_u32_e32 v39, vcc, 0, v39, vcc
	v_lshl_add_u64 v[44:45], v[44:45], 0, v[30:31]
	v_or_b32_e32 v46, s21, v129
	v_add_co_u32_e32 v44, vcc, 0x2000, v44
	v_mad_i64_i32 v[28:29], s[4:5], v46, s35, v[28:29]
	s_nop 0
	v_addc_co_u32_e32 v45, vcc, 0, v45, vcc
	v_lshl_add_u64 v[28:29], v[28:29], 0, v[30:31]
	v_add_co_u32_e32 v28, vcc, 0x2000, v28
	s_mov_b32 s4, 12
	s_nop 0
	v_addc_co_u32_e32 v29, vcc, 0, v29, vcc
	global_load_dwordx4 v[16:19], v[16:17], off offset:2048
	s_nop 0
	global_load_dwordx4 v[20:23], v[20:21], off offset:2048
	s_nop 0
	global_load_dwordx4 v[24:27], v[24:25], off offset:2048
	s_nop 0
	global_load_dwordx4 v[32:35], v[32:33], off offset:2048
	s_nop 0
	global_load_dwordx4 v[40:43], v[36:37], off offset:2048
	s_nop 0
	global_load_dwordx4 v[36:39], v[38:39], off offset:2048
	s_nop 0
	global_load_dwordx4 v[44:47], v[44:45], off offset:2048
	s_nop 0
	global_load_dwordx4 v[28:31], v[28:29], off offset:2048
	s_ashr_i32 s5, s4, 31
	s_lshl_b64 s[4:5], s[4:5], 3
	s_add_u32 s4, s0, s4
	s_addc_u32 s5, s1, s5
	s_load_dwordx2 s[4:5], s[4:5], 0x0
	s_mov_b32 s28, 13
	v_lshlrev_b64 v[64:65], 2, v[48:49]
	s_movk_i32 s21, 0x4000
	s_waitcnt lgkmcnt(0)
	s_add_u32 s4, s4, s76
	s_addc_u32 s5, s5, s77
	s_ashr_i32 s29, s28, 31
	s_lshl_b64 s[28:29], s[28:29], 3
	s_add_u32 s28, s0, s28
	s_addc_u32 s29, s1, s29
	s_load_dwordx2 s[28:29], s[28:29], 0x0
	v_lshl_add_u64 v[60:61], s[4:5], 0, v[64:65]
	v_add_co_u32_e32 v50, vcc, s21, v60
	s_mov_b32 s21, 0x8000
	s_waitcnt lgkmcnt(0)
	s_add_u32 s4, s28, s78
	s_addc_u32 s5, s29, s79
	s_mov_b64 s[28:29], 0x4000
	v_addc_co_u32_e32 v51, vcc, 0, v61, vcc
	v_lshl_add_u64 v[48:49], v[60:61], 0, s[28:29]
	s_mov_b64 s[28:29], 0x8000
	v_add_co_u32_e32 v58, vcc, s21, v60
	v_lshl_add_u64 v[56:57], v[60:61], 0, s[28:29]
	s_nop 0
	v_addc_co_u32_e32 v59, vcc, 0, v61, vcc
	s_mov_b64 s[28:29], 0xc000
	global_load_dwordx4 v[52:55], v[60:61], off offset:16
	global_load_dwordx4 v[72:75], v[60:61], off
	v_lshl_add_u64 v[62:63], v[60:61], 0, s[28:29]
	v_add_co_u32_e32 v60, vcc, 0xc000, v60
	v_lshl_add_u64 v[84:85], s[4:5], 0, v[64:65]
	s_nop 0
	v_addc_co_u32_e32 v61, vcc, 0, v61, vcc
	global_load_dwordx4 v[68:71], v[50:51], off
	s_nop 0
	global_load_dwordx4 v[48:51], v[48:49], off offset:16
	s_nop 0
	global_load_dwordx4 v[76:79], v[58:59], off
	s_nop 0
	global_load_dwordx4 v[56:59], v[56:57], off offset:16
	s_nop 0
	global_load_dwordx4 v[80:83], v[60:61], off
	s_nop 0
	global_load_dwordx4 v[60:63], v[62:63], off offset:16
	s_nop 0
	global_load_dwordx4 v[64:67], v[84:85], off offset:16
	s_nop 0
	global_load_dwordx4 v[84:87], v[84:85], off
	s_and_saveexec_b64 s[98:99], s[40:41]
	s_cbranch_execz .Ls1_dt_done
	s_lshl_b32 s100, s87, 6
	v_or_b32_e32 v174, s100, v108
	v_ashrrev_i32_e32 v175, 31, v174
	v_readlane_b32 s4, v252, 25
	v_lshl_add_u32 v172, s2, 2, v109
	v_lshlrev_b64 v[174:175], 7, v[174:175]
	v_readlane_b32 s5, v252, 26
	v_ashrrev_i32_e32 v173, 31, v172
	s_nop 0
	v_lshl_add_u64 v[174:175], s[4:5], 0, v[174:175]
	v_lshl_add_u64 v[174:175], v[172:173], 2, v[174:175]
	s_mov_b32 s4, 14
	global_load_dword v173, v[174:175], off
	s_ashr_i32 s5, s4, 31
	s_lshl_b64 s[4:5], s[4:5], 3
	s_add_u32 s4, s0, s4
	s_addc_u32 s5, s1, s5
	s_load_dwordx2 s[4:5], s[4:5], 0x0
	v_add_u32_e32 v174, s18, v172
	v_ashrrev_i32_e32 v175, 31, v174
	s_waitcnt lgkmcnt(0)
	v_lshl_add_u64 v[176:177], v[174:175], 2, s[4:5]
	global_load_dword v176, v[176:177], off
	s_mov_b32 s4, 0x41a00000
	s_waitcnt vmcnt(0)
	v_add_f32_e32 v173, v173, v176
	v_cmp_nlt_f32_e32 vcc, s4, v173
	s_and_saveexec_b64 s[4:5], vcc
	s_cbranch_execz .LBB0_332
; __device__ __forceinline__ const float* inp(const Params& p, int i) { asm volatile("" : "+s"(i)); return p.in[i]; }
; __device__ __forceinline__ float softplus_f(float x) { return x > 20.f ? x : log1pf(expf(x)); }
; __device__ __forceinline__ void dt_acum(const Params& p, int layer, int c, int h, int lane, float& dtv, float& acum, float& total) {
;     const float* DT = (const float*)(p.ws + WS_DT);
;     const float raw = DT[(size_t)(c * 64 + lane) * 32 + h];
;     dtv = softplus_f(raw + inp(p, 14)[layer * 32 + h]);
;     const float A = -expf(inp(p, 15)[layer * 32 + h]);
	v_mul_f32_e32 v176, 0x3fb8aa3b, v173
	v_rndne_f32_e32 v177, v176
	s_mov_b32 s32, 0x3fb8aa3b
	v_sub_f32_e32 v178, v176, v177
	v_fma_f32 v176, v173, s32, -v176
	v_fmac_f32_e32 v176, 0x32a5705f, v173
	v_add_f32_e32 v176, v178, v176
	v_cvt_i32_f32_e32 v177, v177
	v_exp_f32_e32 v176, v176
	s_mov_b32 s32, 0xc2ce8ed0
	v_cmp_ngt_f32_e32 vcc, s32, v173
	s_mov_b32 s32, 0x42b17218
	v_ldexp_f32 v176, v176, v177
	v_cndmask_b32_e32 v176, 0, v176, vcc
	v_cmp_nlt_f32_e32 vcc, s32, v173
	s_mov_b32 s32, 0x3f2aaaab
	s_nop 0
	v_cndmask_b32_e32 v173, v162, v176, vcc
	v_add_f32_e32 v178, 1.0, v173
	v_add_f32_e32 v176, -1.0, v178
	v_sub_f32_e32 v177, v176, v178
	v_add_f32_e32 v177, 1.0, v177
	v_sub_f32_e32 v176, v173, v176
	v_add_f32_e32 v179, v176, v177
	v_frexp_mant_f32_e32 v180, v178
	v_cvt_f64_f32_e32 v[176:177], v178
	v_frexp_exp_i32_f64_e32 v176, v[176:177]
	v_cmp_gt_f32_e32 vcc, s32, v180
	s_mov_b32 s32, 0x3f317218
	s_nop 0
	v_subbrev_co_u32_e32 v184, vcc, 0, v176, vcc
	v_sub_u32_e32 v176, 0, v184
	v_ldexp_f32 v177, v178, v176
	v_add_f32_e32 v178, -1.0, v177
	v_add_f32_e32 v180, 1.0, v177
	v_ldexp_f32 v176, v179, v176
	v_add_f32_e32 v179, 1.0, v178
	v_add_f32_e32 v181, -1.0, v180
	v_sub_f32_e32 v179, v177, v179
	v_sub_f32_e32 v177, v177, v181
	v_add_f32_e32 v179, v176, v179
	v_add_f32_e32 v176, v176, v177
	v_add_f32_e32 v185, v180, v176
	v_rcp_f32_e32 v187, v185
	v_sub_f32_e32 v177, v180, v185
	v_add_f32_e32 v186, v176, v177
	v_add_f32_e32 v177, v178, v179
	v_mul_f32_e32 v189, v177, v187
	v_sub_f32_e32 v176, v178, v177
	v_mul_f32_e32 v178, v185, v189
	v_fma_f32 v180, v189, v185, -v178
	v_fmac_f32_e32 v180, v189, v186
	v_add_f32_e32 v188, v179, v176
	v_add_f32_e32 v176, v178, v180
	v_sub_f32_e32 v179, v177, v176
	v_pk_add_f32 v[182:183], v[176:177], v[178:179] neg_lo:[0,1] neg_hi:[0,1]
	v_mov_b32_e32 v181, v176
	v_pk_add_f32 v[176:177], v[182:183], v[180:181] neg_lo:[0,1] neg_hi:[0,1]
	s_nop 0
	v_add_f32_e32 v177, v188, v177
	v_add_f32_e32 v176, v176, v177
	v_add_f32_e32 v177, v179, v176
	v_mul_f32_e32 v188, v187, v177
	v_mul_f32_e32 v178, v185, v188
	v_fma_f32 v180, v188, v185, -v178
	v_fmac_f32_e32 v180, v188, v186
	v_sub_f32_e32 v179, v179, v177
	v_add_f32_e32 v185, v176, v179
	v_add_f32_e32 v176, v178, v180
	v_sub_f32_e32 v179, v177, v176
	v_pk_add_f32 v[182:183], v[176:177], v[178:179] neg_lo:[0,1] neg_hi:[0,1]
	v_mov_b32_e32 v181, v176
	v_pk_add_f32 v[176:177], v[182:183], v[180:181] neg_lo:[0,1] neg_hi:[0,1]
	s_nop 0
	v_add_f32_e32 v177, v185, v177
	v_add_f32_e32 v176, v176, v177
	v_add_f32_e32 v177, v189, v188
	v_add_f32_e32 v176, v179, v176
	v_sub_f32_e32 v178, v177, v189
	v_mul_f32_e32 v176, v187, v176
	v_sub_f32_e32 v178, v188, v178
	v_add_f32_e32 v178, v178, v176
	v_add_f32_e32 v180, v177, v178
	v_mul_f32_e32 v181, v180, v180
	v_fmamk_f32 v176, v181, 0x3e9b6dac, v160
	v_fmaak_f32 v137, v181, v176, 0x3f2aaada
	v_cvt_f32_i32_e32 v176, v184
	v_sub_f32_e32 v177, v180, v177
	v_sub_f32_e32 v177, v178, v177
	v_ldexp_f32 v182, v177, 1
	v_mul_f32_e32 v177, v180, v181
	v_ldexp_f32 v179, v180, 1
	v_pk_mul_f32 v[180:181], v[176:177], v[136:137]
	s_nop 0
	v_fma_f32 v178, v176, s32, -v180
	v_fmac_f32_e32 v178, 0xb102e308, v176
	v_pk_add_f32 v[176:177], v[180:181], v[178:179]
	s_mov_b32 s32, 0x7f800000
	v_sub_f32_e32 v179, v177, v179
	v_sub_f32_e32 v179, v181, v179
	v_add_f32_e32 v183, v182, v179
	v_mov_b32_e32 v182, v180
	v_pk_add_f32 v[180:181], v[176:177], v[180:181] neg_lo:[0,1] neg_hi:[0,1]
	v_pk_add_f32 v[184:185], v[176:177], v[182:183]
	v_mov_b32_e32 v179, v176
	v_mov_b32_e32 v181, v185
	v_pk_add_f32 v[186:187], v[178:179], v[180:181] neg_lo:[0,1] neg_hi:[0,1]
	v_pk_add_f32 v[178:179], v[178:179], v[180:181]
	v_mov_b32_e32 v182, v183
	v_pk_add_f32 v[180:181], v[178:179], v[176:177] op_sel:[1,0] op_sel_hi:[0,1] neg_lo:[0,1] neg_hi:[0,1]
	v_pk_add_f32 v[188:189], v[184:185], v[180:181] op_sel_hi:[1,0] neg_lo:[0,1] neg_hi:[0,1]
	v_mov_b32_e32 v184, v185
	v_mov_b32_e32 v185, v179
	v_pk_mov_b32 v[180:181], v[176:177], v[180:181] op_sel:[1,0]
	v_mov_b32_e32 v183, v176
	v_pk_add_f32 v[180:181], v[184:185], v[180:181] neg_lo:[0,1] neg_hi:[0,1]
	v_mov_b32_e32 v188, v186
	v_pk_add_f32 v[176:177], v[182:183], v[180:181] neg_lo:[0,1] neg_hi:[0,1]
	v_mov_b32_e32 v187, v179
	v_pk_add_f32 v[180:181], v[188:189], v[176:177]
	v_cmp_neq_f32_e32 vcc, s32, v173
	v_pk_add_f32 v[182:183], v[180:181], v[180:181] op_sel:[0,1] op_sel_hi:[1,0]
	s_mov_b32 s32, 0x33800000
	v_pk_add_f32 v[178:179], v[178:179], v[182:183] op_sel:[1,0] op_sel_hi:[0,1]
	v_mov_b32_e32 v181, v178
	v_pk_add_f32 v[184:185], v[180:181], v[186:187] neg_lo:[0,1] neg_hi:[0,1]
	v_mov_b32_e32 v177, v182
	v_sub_f32_e32 v179, v180, v184
	v_pk_add_f32 v[176:177], v[176:177], v[184:185] neg_lo:[0,1] neg_hi:[0,1]
	v_sub_f32_e32 v179, v186, v179
	v_add_f32_e32 v176, v176, v179
	v_add_f32_e32 v176, v176, v177
	v_add_f32_e32 v176, v178, v176
	v_cndmask_b32_e32 v176, v162, v176, vcc
	v_cmp_lt_f32_e64 vcc, |v173|, s32
	s_nop 1
	v_cndmask_b32_e32 v173, v176, v173, vcc
; __device__ __forceinline__ const float* inp(const Params& p, int i) { asm volatile("" : "+s"(i)); return p.in[i]; }
; __device__ __forceinline__ void dt_acum(const Params& p, int layer, int c, int h, int lane, float& dtv, float& acum, float& total) {
;     ...
;     const float A = -expf(inp(p, 15)[layer * 32 + h]);
;     float a = dtv * A;
; #pragma unroll
;     for (int o = 1; o < 64; o <<= 1) { const float t = __shfl_up(a, o); if (lane >= o) a += t; }
;     acum = a; total = __shfl(a, 63);
; }
; __device__ void phase_s1(const Params& p, int layer, unsigned char* lds) {
;     ...
;             dt_acum(p, layer, c, h, lane, dtv, acum, total);
;             s_w[wave * 64 + lane] = dtv * __expf(total - acum);
;             if (lane == 0) DEC[c * 32 + h] = __expf(total);
;         }
;         __syncthreads();
.LBB0_332:
	s_or_b64 exec, exec, s[4:5]
	s_mov_b32 s4, 15
	s_ashr_i32 s5, s4, 31
	s_lshl_b64 s[4:5], s[4:5], 3
	s_add_u32 s4, s0, s4
	s_addc_u32 s5, s1, s5
	s_load_dwordx2 s[4:5], s[4:5], 0x0
	s_waitcnt lgkmcnt(0)
	v_lshl_add_u64 v[174:175], v[174:175], 2, s[4:5]
	global_load_dword v174, v[174:175], off
	s_mov_b32 s4, 0x3fb8aa3b
	s_waitcnt vmcnt(0)
	v_mul_f32_e32 v175, 0x3fb8aa3b, v174
	v_fma_f32 v176, v174, s4, -v175
	v_rndne_f32_e32 v177, v175
	v_fmac_f32_e32 v176, 0x32a5705f, v174
	v_sub_f32_e32 v175, v175, v177
	v_add_f32_e32 v175, v175, v176
	v_exp_f32_e32 v175, v175
	v_cvt_i32_f32_e32 v176, v177
	s_mov_b32 s4, 0xc2ce8ed0
	v_cmp_ngt_f32_e32 vcc, s4, v174
	s_mov_b32 s4, 0x42b17218
	v_ldexp_f32 v175, v175, v176
	v_cndmask_b32_e32 v175, 0, v175, vcc
	v_cmp_nlt_f32_e32 vcc, s4, v174
	v_add_u32_e32 v176, -1, v161
	s_nop 0
	v_cndmask_b32_e32 v174, v162, v175, vcc
	v_cmp_lt_i32_e32 vcc, v176, v163
	v_mul_f32_e64 v175, v173, -v174
	s_nop 0
	v_cndmask_b32_e32 v176, v176, v161, vcc
	v_lshlrev_b32_e32 v176, 2, v176
	ds_bpermute_b32 v176, v176, v175
	s_waitcnt lgkmcnt(0)
	v_fma_f32 v174, v173, -v174, v176
	v_cndmask_b32_e64 v174, v174, v175, s[42:43]
	v_add_u32_e32 v175, -2, v161
	v_cmp_lt_i32_e32 vcc, v175, v163
	s_nop 1
	v_cndmask_b32_e32 v175, v175, v161, vcc
	v_lshlrev_b32_e32 v175, 2, v175
	ds_bpermute_b32 v175, v175, v174
	s_waitcnt lgkmcnt(0)
	v_add_f32_e32 v175, v174, v175
	v_cndmask_b32_e64 v174, v175, v174, s[44:45]
	v_add_u32_e32 v175, -4, v161
	v_cmp_lt_i32_e32 vcc, v175, v163
	s_nop 1
	v_cndmask_b32_e32 v175, v175, v161, vcc
	v_lshlrev_b32_e32 v175, 2, v175
	ds_bpermute_b32 v175, v175, v174
	s_waitcnt lgkmcnt(0)
	v_add_f32_e32 v175, v174, v175
	v_cndmask_b32_e64 v174, v175, v174, s[46:47]
	v_add_u32_e32 v175, -8, v161
	v_cmp_lt_i32_e32 vcc, v175, v163
	s_nop 1
	v_cndmask_b32_e32 v175, v175, v161, vcc
	v_lshlrev_b32_e32 v175, 2, v175
	ds_bpermute_b32 v175, v175, v174
	s_waitcnt lgkmcnt(0)
	v_add_f32_e32 v175, v174, v175
	v_cndmask_b32_e64 v174, v175, v174, s[48:49]
	v_add_u32_e32 v175, -16, v161
	v_cmp_lt_i32_e32 vcc, v175, v163
	s_nop 1
	v_cndmask_b32_e32 v175, v175, v161, vcc
	v_lshlrev_b32_e32 v175, 2, v175
	ds_bpermute_b32 v175, v175, v174
	s_waitcnt lgkmcnt(0)
	v_add_f32_e32 v175, v174, v175
	v_cndmask_b32_e64 v174, v175, v174, s[50:51]
	v_subrev_u32_e32 v175, 32, v161
	v_cmp_lt_i32_e32 vcc, v175, v163
	s_nop 1
	v_cndmask_b32_e32 v175, v175, v161, vcc
	v_lshlrev_b32_e32 v175, 2, v175
	ds_bpermute_b32 v175, v175, v174
	s_waitcnt lgkmcnt(0)
	v_add_f32_e32 v175, v174, v175
	v_cndmask_b32_e64 v175, v175, v174, s[68:69]
	ds_bpermute_b32 v174, v251, v175
	s_waitcnt lgkmcnt(0)
	v_sub_f32_e32 v175, v174, v175
	v_mul_f32_e32 v175, 0x3fb8aa3b, v175
	v_exp_f32_e32 v175, v175
	s_nop 0
	v_mul_f32_e32 v173, v173, v175
	ds_write_b32 v110, v173 offset:55296
	s_and_b64 exec, exec, s[42:43]
	s_cbranch_execz .Ls1_dt_done
	v_mul_f32_e32 v173, 0x3fb8aa3b, v174
	v_exp_f32_e32 v174, v173
	v_lshl_add_u32 v172, s87, 5, v172
	v_readlane_b32 s4, v252, 34
	v_ashrrev_i32_e32 v173, 31, v172
	v_readlane_b32 s5, v252, 35
	s_nop 1
	v_lshl_add_u64 v[172:173], v[172:173], 2, s[4:5]
	global_store_dword v[172:173], v174, off
.Ls1_dt_done:
	s_or_b64 exec, exec, s[98:99]
	s_waitcnt lgkmcnt(0)
	s_barrier
	v_mov_b32_e32 v103, 1.0
	v_mov_b32_e32 v102, 1.0
	s_and_saveexec_b64 s[4:5], s[56:57]
	ds_read_b32 v102, v119 offset:55296
	s_or_b64 exec, exec, s[4:5]
	s_and_saveexec_b64 s[4:5], s[56:57]
	ds_read_b32 v103, v119 offset:55300
	s_or_b64 exec, exec, s[4:5]
	v_mov_b32_e32 v101, 1.0
	v_mov_b32_e32 v100, 1.0
	s_and_saveexec_b64 s[4:5], s[56:57]
	ds_read_b32 v100, v119 offset:55304
	s_or_b64 exec, exec, s[4:5]
	s_and_saveexec_b64 s[4:5], s[56:57]
	ds_read_b32 v101, v119 offset:55308
	s_or_b64 exec, exec, s[4:5]
	v_mov_b32_e32 v105, 1.0
	v_mov_b32_e32 v104, 1.0
	s_and_saveexec_b64 s[4:5], s[56:57]
	ds_read_b32 v104, v119 offset:55312
	s_or_b64 exec, exec, s[4:5]
	s_and_saveexec_b64 s[4:5], s[56:57]
	ds_read_b32 v105, v119 offset:55316
	s_or_b64 exec, exec, s[4:5]
	v_mov_b32_e32 v107, 1.0
	v_mov_b32_e32 v106, 1.0
	s_and_saveexec_b64 s[4:5], s[56:57]
	ds_read_b32 v106, v119 offset:55320
	s_or_b64 exec, exec, s[4:5]
	s_and_saveexec_b64 s[4:5], s[56:57]
	s_cbranch_execz .LBB0_327
	ds_read_b32 v107, v119 offset:55324
	s_branch .LBB0_327
